# P4b output-projection epilogue hand-written: gate loaded once per unit, X row loads as a rolling 3-deep pipeline with counted vmcnt waits (was 16 serialized load-wait-store groups); arithmetic unchang
# baseline (speedup 1.0000x reference)
; __device__ __forceinline__ int opq(int v) { asm volatile("" : "+v"(v)); return v; }
;     __device__ __forceinline__ void operator()(EPI_ARGS) const {
;         EPI_RECOMPUTE
;         const int row0 = u.pm * 256 + wr * 64 + fr; const float ALPHA = 1.189207115002721f;
;         const float* gate = MOD + (size_t)(u.pm >> 5) * 3072 + 2048;
; #pragma unroll
;         for (int ai = 0; ai < 2; ++ai)
; #pragma unroll
;             for (int m = 0; m < 4; ++m) {
;                 __builtin_amdgcn_sched_barrier(0); const int row = opq(row0 + ai * 128 + m * 16);
; #pragma unroll
;                 for (int bj = 0; bj < 2; ++bj) {
;                     const int c0 = u.pn * 256 + bj * 128 + wc * 32 + 8 * fq;
;                     const f32x4 x0 = *(const f32x4*)(X + (size_t)row * 1024 + c0), x1 = *(const f32x4*)(X + (size_t)row * 1024 + c0 + 4);
;                     const f32x4 g0 = *(const f32x4*)(gate + c0), g1 = *(const f32x4*)(gate + c0 + 4);
;                     *(f32x4*)(OUT + (size_t)row * 1024 + c0) = x0 * ALPHA + g0 * acc[ai][bj][m][0];
;                     *(f32x4*)(OUT + (size_t)row * 1024 + c0 + 4) = x1 * ALPHA + g1 * acc[ai][bj][m][1];
;                 }
.LBB0_1413:
	s_lshl_b32 s9, s16, 8
	s_add_i32 s9, s9, s33
	v_mbcnt_lo_u32_b32 v144, -1, 0
	v_mbcnt_hi_u32_b32 v144, -1, v144
	s_nop 0
	v_and_or_b32 v154, v144, 15, s9
	s_ashr_i32 s9, s16, 5
	s_mul_hi_i32 s11, s9, 0x3000
	s_mulk_i32 s9, 0x3000
	s_add_u32 s9, s2, s9
	s_addc_u32 s11, s3, s11
	s_add_u32 s42, s9, 0x2000
	s_addc_u32 s43, s11, 0
	s_lshl_b32 s9, s53, 8
	v_ashrrev_i32_e32 v144, 1, v144
	v_and_b32_e32 v144, -8, v144
	s_or_b32 s9, s9, s80
	v_add_u32_e32 v146, s9, v144
	v_ashrrev_i32_e32 v147, 31, v146
	v_lshlrev_b64 v[144:145], 2, v[146:147]
	v_lshl_add_u64 v[148:149], s[42:43], 0, v[144:145]
	global_load_dwordx4 v[156:159], v[148:149], off
	global_load_dwordx4 v[160:163], v[148:149], off offset:16
	global_load_dwordx4 v[164:167], v[148:149], off offset:512
	global_load_dwordx4 v[168:171], v[148:149], off offset:528
	v_lshlrev_b32_e32 v155, 12, v154
	v_mov_b32_e32 v221, 0
	v_lshl_add_u64 v[148:149], s[24:25], 0, v[144:145]
	v_lshl_add_u64 v[144:145], s[36:37], 0, v[144:145]
	v_mov_b32_e32 v220, v155
	v_lshl_add_u64 v[146:147], v[220:221], 0, v[144:145]
	global_load_dwordx4 v[172:175], v[146:147], off
	global_load_dwordx4 v[176:179], v[146:147], off offset:16
	global_load_dwordx4 v[180:183], v[146:147], off offset:512
	global_load_dwordx4 v[184:187], v[146:147], off offset:528
	v_add_u32_e32 v220, 0x10000, v155
	v_lshl_add_u64 v[146:147], v[220:221], 0, v[144:145]
	global_load_dwordx4 v[188:191], v[146:147], off
	global_load_dwordx4 v[192:195], v[146:147], off offset:16
	global_load_dwordx4 v[196:199], v[146:147], off offset:512
	global_load_dwordx4 v[200:203], v[146:147], off offset:528
	v_add_u32_e32 v220, 0x20000, v155
	v_lshl_add_u64 v[146:147], v[220:221], 0, v[144:145]
	global_load_dwordx4 v[204:207], v[146:147], off
	global_load_dwordx4 v[208:211], v[146:147], off offset:16
	global_load_dwordx4 v[212:215], v[146:147], off offset:512
	global_load_dwordx4 v[216:219], v[146:147], off offset:528
	s_waitcnt vmcnt(8)
	v_pk_mul_f32 v[124:125], v[124:125], v[156:157]
	v_pk_mul_f32 v[126:127], v[126:127], v[158:159]
	v_pk_mul_f32 v[120:121], v[120:121], v[160:161]
	v_pk_mul_f32 v[122:123], v[122:123], v[162:163]
	v_pk_mul_f32 v[116:117], v[116:117], v[164:165]
	v_pk_mul_f32 v[118:119], v[118:119], v[166:167]
	v_pk_mul_f32 v[112:113], v[112:113], v[168:169]
	v_pk_mul_f32 v[114:115], v[114:115], v[170:171]
	v_pk_fma_f32 v[124:125], v[172:173], s[6:7], v[124:125] op_sel_hi:[1,0,1]
	v_pk_fma_f32 v[126:127], v[174:175], s[6:7], v[126:127] op_sel_hi:[1,0,1]
	v_pk_fma_f32 v[120:121], v[176:177], s[6:7], v[120:121] op_sel_hi:[1,0,1]
	v_pk_fma_f32 v[122:123], v[178:179], s[6:7], v[122:123] op_sel_hi:[1,0,1]
	v_pk_fma_f32 v[116:117], v[180:181], s[6:7], v[116:117] op_sel_hi:[1,0,1]
	v_pk_fma_f32 v[118:119], v[182:183], s[6:7], v[118:119] op_sel_hi:[1,0,1]
	v_pk_fma_f32 v[112:113], v[184:185], s[6:7], v[112:113] op_sel_hi:[1,0,1]
	v_pk_fma_f32 v[114:115], v[186:187], s[6:7], v[114:115] op_sel_hi:[1,0,1]
	v_mov_b32_e32 v220, v155
	v_lshl_add_u64 v[146:147], v[220:221], 0, v[148:149]
	global_store_dwordx4 v[146:147], v[124:127], off
	global_store_dwordx4 v[146:147], v[120:123], off offset:16
	global_store_dwordx4 v[146:147], v[116:119], off offset:512
	global_store_dwordx4 v[146:147], v[112:115], off offset:528
	v_add_u32_e32 v220, 0x30000, v155
	v_lshl_add_u64 v[146:147], v[220:221], 0, v[144:145]
	global_load_dwordx4 v[172:175], v[146:147], off
	global_load_dwordx4 v[176:179], v[146:147], off offset:16
	global_load_dwordx4 v[180:183], v[146:147], off offset:512
	global_load_dwordx4 v[184:187], v[146:147], off offset:528
	s_waitcnt vmcnt(12)
	v_pk_mul_f32 v[108:109], v[108:109], v[156:157]
	v_pk_mul_f32 v[110:111], v[110:111], v[158:159]
	v_pk_mul_f32 v[104:105], v[104:105], v[160:161]
	v_pk_mul_f32 v[106:107], v[106:107], v[162:163]
	v_pk_mul_f32 v[100:101], v[100:101], v[164:165]
	v_pk_mul_f32 v[102:103], v[102:103], v[166:167]
	v_pk_mul_f32 v[96:97], v[96:97], v[168:169]
	v_pk_mul_f32 v[98:99], v[98:99], v[170:171]
	v_pk_fma_f32 v[108:109], v[188:189], s[6:7], v[108:109] op_sel_hi:[1,0,1]
	v_pk_fma_f32 v[110:111], v[190:191], s[6:7], v[110:111] op_sel_hi:[1,0,1]
	v_pk_fma_f32 v[104:105], v[192:193], s[6:7], v[104:105] op_sel_hi:[1,0,1]
	v_pk_fma_f32 v[106:107], v[194:195], s[6:7], v[106:107] op_sel_hi:[1,0,1]
	v_pk_fma_f32 v[100:101], v[196:197], s[6:7], v[100:101] op_sel_hi:[1,0,1]
	v_pk_fma_f32 v[102:103], v[198:199], s[6:7], v[102:103] op_sel_hi:[1,0,1]
	v_pk_fma_f32 v[96:97], v[200:201], s[6:7], v[96:97] op_sel_hi:[1,0,1]
	v_pk_fma_f32 v[98:99], v[202:203], s[6:7], v[98:99] op_sel_hi:[1,0,1]
	v_add_u32_e32 v220, 0x10000, v155
	v_lshl_add_u64 v[146:147], v[220:221], 0, v[148:149]
	global_store_dwordx4 v[146:147], v[108:111], off
	global_store_dwordx4 v[146:147], v[104:107], off offset:16
	global_store_dwordx4 v[146:147], v[100:103], off offset:512
	global_store_dwordx4 v[146:147], v[96:99], off offset:528
	v_add_u32_e32 v220, 0x80000, v155
	v_lshl_add_u64 v[146:147], v[220:221], 0, v[144:145]
	global_load_dwordx4 v[188:191], v[146:147], off
	global_load_dwordx4 v[192:195], v[146:147], off offset:16
	global_load_dwordx4 v[196:199], v[146:147], off offset:512
	global_load_dwordx4 v[200:203], v[146:147], off offset:528
	s_waitcnt vmcnt(16)
; __device__ __forceinline__ int opq(int v) { asm volatile("" : "+v"(v)); return v; }
;     __device__ __forceinline__ void operator()(EPI_ARGS) const {
;     ...
;                 __builtin_amdgcn_sched_barrier(0); const int row = opq(row0 + ai * 128 + m * 16);
; #pragma unroll
;                 for (int bj = 0; bj < 2; ++bj) {
;                     const int c0 = u.pn * 256 + bj * 128 + wc * 32 + 8 * fq;
;                     const f32x4 x0 = *(const f32x4*)(X + (size_t)row * 1024 + c0), x1 = *(const f32x4*)(X + (size_t)row * 1024 + c0 + 4);
;                     const f32x4 g0 = *(const f32x4*)(gate + c0), g1 = *(const f32x4*)(gate + c0 + 4);
;                     *(f32x4*)(OUT + (size_t)row * 1024 + c0) = x0 * ALPHA + g0 * acc[ai][bj][m][0];
;                     *(f32x4*)(OUT + (size_t)row * 1024 + c0 + 4) = x1 * ALPHA + g1 * acc[ai][bj][m][1];
;                 }
	v_pk_mul_f32 v[92:93], v[92:93], v[156:157]
	v_pk_mul_f32 v[94:95], v[94:95], v[158:159]
	v_pk_mul_f32 v[88:89], v[88:89], v[160:161]
	v_pk_mul_f32 v[90:91], v[90:91], v[162:163]
	v_pk_mul_f32 v[84:85], v[84:85], v[164:165]
	v_pk_mul_f32 v[86:87], v[86:87], v[166:167]
	v_pk_mul_f32 v[80:81], v[80:81], v[168:169]
	v_pk_mul_f32 v[82:83], v[82:83], v[170:171]
	v_pk_fma_f32 v[92:93], v[204:205], s[6:7], v[92:93] op_sel_hi:[1,0,1]
	v_pk_fma_f32 v[94:95], v[206:207], s[6:7], v[94:95] op_sel_hi:[1,0,1]
	v_pk_fma_f32 v[88:89], v[208:209], s[6:7], v[88:89] op_sel_hi:[1,0,1]
	v_pk_fma_f32 v[90:91], v[210:211], s[6:7], v[90:91] op_sel_hi:[1,0,1]
	v_pk_fma_f32 v[84:85], v[212:213], s[6:7], v[84:85] op_sel_hi:[1,0,1]
	v_pk_fma_f32 v[86:87], v[214:215], s[6:7], v[86:87] op_sel_hi:[1,0,1]
	v_pk_fma_f32 v[80:81], v[216:217], s[6:7], v[80:81] op_sel_hi:[1,0,1]
	v_pk_fma_f32 v[82:83], v[218:219], s[6:7], v[82:83] op_sel_hi:[1,0,1]
	v_add_u32_e32 v220, 0x20000, v155
	v_lshl_add_u64 v[146:147], v[220:221], 0, v[148:149]
	global_store_dwordx4 v[146:147], v[92:95], off
	global_store_dwordx4 v[146:147], v[88:91], off offset:16
	global_store_dwordx4 v[146:147], v[84:87], off offset:512
	global_store_dwordx4 v[146:147], v[80:83], off offset:528
	v_add_u32_e32 v220, 0x90000, v155
	v_lshl_add_u64 v[146:147], v[220:221], 0, v[144:145]
	global_load_dwordx4 v[204:207], v[146:147], off
	global_load_dwordx4 v[208:211], v[146:147], off offset:16
	global_load_dwordx4 v[212:215], v[146:147], off offset:512
	global_load_dwordx4 v[216:219], v[146:147], off offset:528
	s_waitcnt vmcnt(16)
	v_pk_mul_f32 v[76:77], v[76:77], v[156:157]
	v_pk_mul_f32 v[78:79], v[78:79], v[158:159]
	v_pk_mul_f32 v[72:73], v[72:73], v[160:161]
	v_pk_mul_f32 v[74:75], v[74:75], v[162:163]
	v_pk_mul_f32 v[68:69], v[68:69], v[164:165]
	v_pk_mul_f32 v[70:71], v[70:71], v[166:167]
	v_pk_mul_f32 v[64:65], v[64:65], v[168:169]
	v_pk_mul_f32 v[66:67], v[66:67], v[170:171]
	v_pk_fma_f32 v[76:77], v[172:173], s[6:7], v[76:77] op_sel_hi:[1,0,1]
	v_pk_fma_f32 v[78:79], v[174:175], s[6:7], v[78:79] op_sel_hi:[1,0,1]
	v_pk_fma_f32 v[72:73], v[176:177], s[6:7], v[72:73] op_sel_hi:[1,0,1]
	v_pk_fma_f32 v[74:75], v[178:179], s[6:7], v[74:75] op_sel_hi:[1,0,1]
	v_pk_fma_f32 v[68:69], v[180:181], s[6:7], v[68:69] op_sel_hi:[1,0,1]
	v_pk_fma_f32 v[70:71], v[182:183], s[6:7], v[70:71] op_sel_hi:[1,0,1]
	v_pk_fma_f32 v[64:65], v[184:185], s[6:7], v[64:65] op_sel_hi:[1,0,1]
	v_pk_fma_f32 v[66:67], v[186:187], s[6:7], v[66:67] op_sel_hi:[1,0,1]
	v_add_u32_e32 v220, 0x30000, v155
	v_lshl_add_u64 v[146:147], v[220:221], 0, v[148:149]
	global_store_dwordx4 v[146:147], v[76:79], off
	global_store_dwordx4 v[146:147], v[72:75], off offset:16
	global_store_dwordx4 v[146:147], v[68:71], off offset:512
	global_store_dwordx4 v[146:147], v[64:67], off offset:528
	v_add_u32_e32 v220, 0xa0000, v155
	v_lshl_add_u64 v[146:147], v[220:221], 0, v[144:145]
	global_load_dwordx4 v[172:175], v[146:147], off
	global_load_dwordx4 v[176:179], v[146:147], off offset:16
	global_load_dwordx4 v[180:183], v[146:147], off offset:512
	global_load_dwordx4 v[184:187], v[146:147], off offset:528
	s_waitcnt vmcnt(16)
	v_pk_mul_f32 v[60:61], v[60:61], v[156:157]
	v_pk_mul_f32 v[62:63], v[62:63], v[158:159]
	v_pk_mul_f32 v[56:57], v[56:57], v[160:161]
	v_pk_mul_f32 v[58:59], v[58:59], v[162:163]
	v_pk_mul_f32 v[52:53], v[52:53], v[164:165]
	v_pk_mul_f32 v[54:55], v[54:55], v[166:167]
	v_pk_mul_f32 v[48:49], v[48:49], v[168:169]
	v_pk_mul_f32 v[50:51], v[50:51], v[170:171]
	v_pk_fma_f32 v[60:61], v[188:189], s[6:7], v[60:61] op_sel_hi:[1,0,1]
	v_pk_fma_f32 v[62:63], v[190:191], s[6:7], v[62:63] op_sel_hi:[1,0,1]
	v_pk_fma_f32 v[56:57], v[192:193], s[6:7], v[56:57] op_sel_hi:[1,0,1]
	v_pk_fma_f32 v[58:59], v[194:195], s[6:7], v[58:59] op_sel_hi:[1,0,1]
	v_pk_fma_f32 v[52:53], v[196:197], s[6:7], v[52:53] op_sel_hi:[1,0,1]
	v_pk_fma_f32 v[54:55], v[198:199], s[6:7], v[54:55] op_sel_hi:[1,0,1]
	v_pk_fma_f32 v[48:49], v[200:201], s[6:7], v[48:49] op_sel_hi:[1,0,1]
	v_pk_fma_f32 v[50:51], v[202:203], s[6:7], v[50:51] op_sel_hi:[1,0,1]
	v_add_u32_e32 v220, 0x80000, v155
	v_lshl_add_u64 v[146:147], v[220:221], 0, v[148:149]
	global_store_dwordx4 v[146:147], v[60:63], off
	global_store_dwordx4 v[146:147], v[56:59], off offset:16
	global_store_dwordx4 v[146:147], v[52:55], off offset:512
	global_store_dwordx4 v[146:147], v[48:51], off offset:528
	v_add_u32_e32 v220, 0xb0000, v155
	v_lshl_add_u64 v[146:147], v[220:221], 0, v[144:145]
	global_load_dwordx4 v[188:191], v[146:147], off
	global_load_dwordx4 v[192:195], v[146:147], off offset:16
	global_load_dwordx4 v[196:199], v[146:147], off offset:512
	global_load_dwordx4 v[200:203], v[146:147], off offset:528
	s_waitcnt vmcnt(16)
; __device__ __forceinline__ int opq(int v) { asm volatile("" : "+v"(v)); return v; }
;     __device__ __forceinline__ void operator()(EPI_ARGS) const {
;     ...
;                 __builtin_amdgcn_sched_barrier(0); const int row = opq(row0 + ai * 128 + m * 16);
; #pragma unroll
;                 for (int bj = 0; bj < 2; ++bj) {
;                     const int c0 = u.pn * 256 + bj * 128 + wc * 32 + 8 * fq;
;                     const f32x4 x0 = *(const f32x4*)(X + (size_t)row * 1024 + c0), x1 = *(const f32x4*)(X + (size_t)row * 1024 + c0 + 4);
;                     const f32x4 g0 = *(const f32x4*)(gate + c0), g1 = *(const f32x4*)(gate + c0 + 4);
;                     *(f32x4*)(OUT + (size_t)row * 1024 + c0) = x0 * ALPHA + g0 * acc[ai][bj][m][0];
;                     *(f32x4*)(OUT + (size_t)row * 1024 + c0 + 4) = x1 * ALPHA + g1 * acc[ai][bj][m][1];
;                 }
	v_pk_mul_f32 v[44:45], v[44:45], v[156:157]
	v_pk_mul_f32 v[46:47], v[46:47], v[158:159]
	v_pk_mul_f32 v[40:41], v[40:41], v[160:161]
	v_pk_mul_f32 v[42:43], v[42:43], v[162:163]
	v_pk_mul_f32 v[36:37], v[36:37], v[164:165]
	v_pk_mul_f32 v[38:39], v[38:39], v[166:167]
	v_pk_mul_f32 v[32:33], v[32:33], v[168:169]
	v_pk_mul_f32 v[34:35], v[34:35], v[170:171]
	v_pk_fma_f32 v[44:45], v[204:205], s[6:7], v[44:45] op_sel_hi:[1,0,1]
	v_pk_fma_f32 v[46:47], v[206:207], s[6:7], v[46:47] op_sel_hi:[1,0,1]
	v_pk_fma_f32 v[40:41], v[208:209], s[6:7], v[40:41] op_sel_hi:[1,0,1]
	v_pk_fma_f32 v[42:43], v[210:211], s[6:7], v[42:43] op_sel_hi:[1,0,1]
	v_pk_fma_f32 v[36:37], v[212:213], s[6:7], v[36:37] op_sel_hi:[1,0,1]
	v_pk_fma_f32 v[38:39], v[214:215], s[6:7], v[38:39] op_sel_hi:[1,0,1]
	v_pk_fma_f32 v[32:33], v[216:217], s[6:7], v[32:33] op_sel_hi:[1,0,1]
	v_pk_fma_f32 v[34:35], v[218:219], s[6:7], v[34:35] op_sel_hi:[1,0,1]
	v_add_u32_e32 v220, 0x90000, v155
	v_lshl_add_u64 v[146:147], v[220:221], 0, v[148:149]
	global_store_dwordx4 v[146:147], v[44:47], off
	global_store_dwordx4 v[146:147], v[40:43], off offset:16
	global_store_dwordx4 v[146:147], v[36:39], off offset:512
	global_store_dwordx4 v[146:147], v[32:35], off offset:528
	s_waitcnt vmcnt(12)
	v_pk_mul_f32 v[28:29], v[28:29], v[156:157]
	v_pk_mul_f32 v[30:31], v[30:31], v[158:159]
	v_pk_mul_f32 v[24:25], v[24:25], v[160:161]
	v_pk_mul_f32 v[26:27], v[26:27], v[162:163]
	v_pk_mul_f32 v[20:21], v[20:21], v[164:165]
	v_pk_mul_f32 v[22:23], v[22:23], v[166:167]
	v_pk_mul_f32 v[16:17], v[16:17], v[168:169]
	v_pk_mul_f32 v[18:19], v[18:19], v[170:171]
	v_pk_fma_f32 v[28:29], v[172:173], s[6:7], v[28:29] op_sel_hi:[1,0,1]
	v_pk_fma_f32 v[30:31], v[174:175], s[6:7], v[30:31] op_sel_hi:[1,0,1]
	v_pk_fma_f32 v[24:25], v[176:177], s[6:7], v[24:25] op_sel_hi:[1,0,1]
	v_pk_fma_f32 v[26:27], v[178:179], s[6:7], v[26:27] op_sel_hi:[1,0,1]
	v_pk_fma_f32 v[20:21], v[180:181], s[6:7], v[20:21] op_sel_hi:[1,0,1]
	v_pk_fma_f32 v[22:23], v[182:183], s[6:7], v[22:23] op_sel_hi:[1,0,1]
	v_pk_fma_f32 v[16:17], v[184:185], s[6:7], v[16:17] op_sel_hi:[1,0,1]
	v_pk_fma_f32 v[18:19], v[186:187], s[6:7], v[18:19] op_sel_hi:[1,0,1]
	v_add_u32_e32 v220, 0xa0000, v155
	v_lshl_add_u64 v[146:147], v[220:221], 0, v[148:149]
	global_store_dwordx4 v[146:147], v[28:31], off
	global_store_dwordx4 v[146:147], v[24:27], off offset:16
	global_store_dwordx4 v[146:147], v[20:23], off offset:512
	global_store_dwordx4 v[146:147], v[16:19], off offset:528
	s_waitcnt vmcnt(8)
	v_pk_mul_f32 v[12:13], v[12:13], v[156:157]
	v_pk_mul_f32 v[14:15], v[14:15], v[158:159]
	v_pk_mul_f32 v[8:9], v[8:9], v[160:161]
	v_pk_mul_f32 v[10:11], v[10:11], v[162:163]
	v_pk_mul_f32 v[4:5], v[4:5], v[164:165]
	v_pk_mul_f32 v[6:7], v[6:7], v[166:167]
	v_pk_mul_f32 v[0:1], v[0:1], v[168:169]
	v_pk_mul_f32 v[2:3], v[2:3], v[170:171]
	v_pk_fma_f32 v[12:13], v[188:189], s[6:7], v[12:13] op_sel_hi:[1,0,1]
	v_pk_fma_f32 v[14:15], v[190:191], s[6:7], v[14:15] op_sel_hi:[1,0,1]
	v_pk_fma_f32 v[8:9], v[192:193], s[6:7], v[8:9] op_sel_hi:[1,0,1]
	v_pk_fma_f32 v[10:11], v[194:195], s[6:7], v[10:11] op_sel_hi:[1,0,1]
	v_pk_fma_f32 v[4:5], v[196:197], s[6:7], v[4:5] op_sel_hi:[1,0,1]
	v_pk_fma_f32 v[6:7], v[198:199], s[6:7], v[6:7] op_sel_hi:[1,0,1]
	v_pk_fma_f32 v[0:1], v[200:201], s[6:7], v[0:1] op_sel_hi:[1,0,1]
	v_pk_fma_f32 v[2:3], v[202:203], s[6:7], v[2:3] op_sel_hi:[1,0,1]
	v_add_u32_e32 v220, 0xb0000, v155
	v_lshl_add_u64 v[146:147], v[220:221], 0, v[148:149]
	global_store_dwordx4 v[146:147], v[12:15], off
	global_store_dwordx4 v[146:147], v[8:11], off offset:16
	global_store_dwordx4 v[146:147], v[4:7], off offset:512
	global_store_dwordx4 v[146:147], v[0:3], off offset:528
	s_andn2_b64 vcc, exec, s[4:5]
	s_mov_b64 s[4:5], -1
	s_cbranch_vccnz .LBB0_1402
	v_readlane_b32 s4, v254, 40
	v_readlane_b32 s5, v254, 41
	s_and_b64 vcc, exec, s[4:5]
	s_cbranch_vccnz .LBB0_1401
	s_barrier
	s_branch .LBB0_1401
